# mixer loops: LDS commit of the next K/V tiles interleaved with the PV MFMAs (diff + retention), first K-fragment reads hoisted above address math in diff
# speedup vs baseline: 1.0120x; 1.0037x over previous
; #define RT_COMMIT(KR, VR, buf) do { LAS unsigned char* bb_ = lds + (buf) * MX_BUF; \
;         if (kcopy) *(LAS u32x4*)(bb_ + krow * KP + kch * 16) = KR; *(LAS u32x4*)(bb_ + MX_KBYTES + vr * VP + vc * 16) = VR; } while (0)
; __device__ __forceinline__ void wg_ret_task(ParamsCP pp, int layer, LAS unsigned char* lds, int b, int h, int qb, int tid_in) {
;     ...
;     for (int st = 0; st < 65; st += 2) {
;         RT_ISSUE(kr0s, vr0s, st + 2); RT_COMPUTE(st, 0); RT_COMMIT(kr1s, vr1s, 1); __syncthreads();
;         if (st + 1 < 65) { RT_ISSUE(kr1s, vr1s, st + 3); RT_COMPUTE(st + 1, 1); RT_COMMIT(kr0s, vr0s, 0); __syncthreads(); }
;     }
.Lprio_r_skip:
	s_waitcnt lgkmcnt(0)
	s_barrier
	s_branch .LBB0_406
.LBB0_404:
	s_waitcnt lgkmcnt(0)
	s_barrier
.LBB0_405:
	s_add_i32 s61, s61, 2
	v_add_u32_e32 v130, 64, v130
	s_sub_i32 s60, s60, 64
	v_add_u32_e32 v132, 64, v132
	s_add_i32 s38, s38, 4
	s_and_b64 vcc, exec, s[76:77]
	s_cbranch_vccnz .LBB0_431

; #define RT_COMMIT(KR, VR, buf) do { LAS unsigned char* bb_ = lds + (buf) * MX_BUF; \
;         if (kcopy) *(LAS u32x4*)(bb_ + krow * KP + kch * 16) = KR; *(LAS u32x4*)(bb_ + MX_KBYTES + vr * VP + vc * 16) = VR; } while (0)
; __device__ __forceinline__ void wg_ret_task(ParamsCP pp, int layer, LAS unsigned char* lds, int b, int h, int qb, int tid_in) {
;     ...
;     __syncthreads();
;     RT_ISSUE(kr0s, vr0s, 0); RT_COMMIT(kr0s, vr0s, 0); RT_ISSUE(kr1s, vr1s, 1);
.LBB0_408:
	s_or_b64 exec, exec, s[4:5]
	ds_read_b128 v[96:99], v134
	ds_read_b128 v[100:103], v134 offset:64
	v_mov_b32_e32 v0, s15
	v_mov_b32_e32 v2, s14
	v_cndmask_b32_e64 v0, v0, v2, s[10:11]
	s_waitcnt lgkmcnt(1)
	v_mfma_f32_16x16x32_bf16 v[104:107], v[96:99], v[4:7], 0
	v_or_b32_e32 v0, v0, v124
	v_lshl_add_u64 v[2:3], v[0:1], 1, v[118:119]
	ds_read_b128 v[108:111], v134 offset:2304
	ds_read_b128 v[138:141], v134 offset:2368
	v_mfma_f32_16x16x32_bf16 v[96:99], v[96:99], v[12:15], 0
	s_cmpk_lg_i32 s60, 0xf800
	s_cselect_b64 s[4:5], -1, 0
	s_cmpk_eq_i32 s60, 0xf800
	s_waitcnt lgkmcnt(2)
	v_mfma_f32_16x16x32_bf16 v[104:107], v[100:103], v[8:11], v[104:107]
	v_add_u32_e32 v137, s60, v133
	v_mov_b32_e32 v0, 0
	v_mfma_f32_16x16x32_bf16 v[100:103], v[100:103], v[16:19], v[96:99]
	s_nop 2
	global_load_dwordx4 v[96:99], v[2:3], off
	s_waitcnt lgkmcnt(1)
	v_mfma_f32_16x16x32_bf16 v[112:115], v[108:111], v[4:7], 0
	v_mov_b32_e32 v2, 0
	v_mfma_f32_16x16x32_bf16 v[108:111], v[108:111], v[12:15], 0
	s_waitcnt lgkmcnt(0)
	v_mfma_f32_16x16x32_bf16 v[112:115], v[138:141], v[8:11], v[112:115]
	v_mfma_f32_16x16x32_bf16 v[108:111], v[138:141], v[16:19], v[108:111]
	ds_read_b64 v[148:149], v135 offset:8704
	ds_read_b64 v[150:151], v135 offset:8736
	ds_read_b64 v[152:153], v135 offset:9984
	ds_read_b64 v[154:155], v135 offset:10016
	ds_read_b64 v[156:157], v135 offset:11264
	ds_read_b64 v[158:159], v135 offset:11296
	ds_read_b64 v[160:161], v135 offset:12544
	ds_read_b64 v[162:163], v135 offset:12576
	ds_read_b64 v[164:165], v135 offset:13824
	ds_read_b64 v[166:167], v135 offset:13856
	ds_read_b64 v[168:169], v135 offset:15104
	ds_read_b64 v[170:171], v135 offset:15136
	ds_read_b64 v[172:173], v135 offset:16384
	ds_read_b64 v[174:175], v135 offset:16416
	v_add_u32_e32 v136, s60, v131
	v_cvt_f32_i32_e32 v180, v137
	v_cvt_f32_i32_e32 v181, v136
	v_mov_b32_e32 v200, v180
	v_add_f32_e32 v201, 0xbf800000, v180
	v_add_f32_e32 v202, 0xc0000000, v180
	v_add_f32_e32 v203, 0xc0400000, v180
	v_mul_f32_e32 v208, v126, v200
	v_mul_f32_e32 v209, v126, v201
	v_mul_f32_e32 v210, v126, v202
	v_mul_f32_e32 v211, v126, v203
	v_mul_f32_e64 v212, v200, -v127
	v_mul_f32_e64 v213, v201, -v127
	v_mul_f32_e64 v214, v202, -v127
	v_mul_f32_e64 v215, v203, -v127
	v_min_f32_e32 v208, v208, v212
	v_min_f32_e32 v209, v209, v213
	v_min_f32_e32 v210, v210, v214
	v_min_f32_e32 v211, v211, v215
	v_exp_f32_e32 v208, v208
	v_exp_f32_e32 v209, v209
	v_exp_f32_e32 v210, v210
	v_exp_f32_e32 v211, v211
	v_mul_f32_e32 v184, v208, v104
	v_mul_f32_e32 v185, v209, v105
	v_mul_f32_e32 v186, v210, v106
	v_mul_f32_e32 v187, v211, v107
	v_add_f32_e32 v200, 0xc1800000, v180
	v_add_f32_e32 v201, 0xc1880000, v180
	v_add_f32_e32 v202, 0xc1900000, v180
	v_add_f32_e32 v203, 0xc1980000, v180
	v_mul_f32_e32 v208, v126, v200
	v_mul_f32_e32 v209, v126, v201
	v_mul_f32_e32 v210, v126, v202
	v_mul_f32_e32 v211, v126, v203
	v_mul_f32_e64 v212, v200, -v127
	v_mul_f32_e64 v213, v201, -v127
	v_mul_f32_e64 v214, v202, -v127
	v_mul_f32_e64 v215, v203, -v127
	v_min_f32_e32 v208, v208, v212
	v_min_f32_e32 v209, v209, v213
	v_min_f32_e32 v210, v210, v214
	v_min_f32_e32 v211, v211, v215
	v_exp_f32_e32 v208, v208
	v_exp_f32_e32 v209, v209
	v_exp_f32_e32 v210, v210
	v_exp_f32_e32 v211, v211
	v_mul_f32_e32 v188, v208, v112
	v_mul_f32_e32 v189, v209, v113
	v_mul_f32_e32 v190, v210, v114
	v_mul_f32_e32 v191, v211, v115
	v_cndmask_b32_e64 v188, 0, v188, s[4:5]
	v_cndmask_b32_e64 v189, 0, v189, s[4:5]
	v_cndmask_b32_e64 v190, 0, v190, s[4:5]
	v_cndmask_b32_e64 v191, 0, v191, s[4:5]
	s_waitcnt lgkmcnt(13)
	ds_read_b64 v[176:177], v135 offset:17664
	ds_read_b64 v[178:179], v135 offset:17696
	v_mov_b32_e32 v200, v181
	v_add_f32_e32 v201, 0xbf800000, v181
	v_add_f32_e32 v202, 0xc0000000, v181
	v_add_f32_e32 v203, 0xc0400000, v181
	v_mul_f32_e32 v208, v126, v200
	v_mul_f32_e32 v209, v126, v201
	v_mul_f32_e32 v210, v126, v202
	v_mul_f32_e32 v211, v126, v203
	v_mul_f32_e64 v212, v200, -v127
	v_mul_f32_e64 v213, v201, -v127
	v_mul_f32_e64 v214, v202, -v127
	v_mul_f32_e64 v215, v203, -v127
	v_min_f32_e32 v208, v208, v212
	v_min_f32_e32 v209, v209, v213
	v_min_f32_e32 v210, v210, v214
	v_min_f32_e32 v211, v211, v215
	v_exp_f32_e32 v208, v208
	v_exp_f32_e32 v209, v209
	v_exp_f32_e32 v210, v210
	v_exp_f32_e32 v211, v211
	v_mul_f32_e32 v192, v208, v100
	v_mul_f32_e32 v193, v209, v101
	v_mul_f32_e32 v194, v210, v102
	v_mul_f32_e32 v195, v211, v103
	v_add_f32_e32 v200, 0xc1800000, v181
	v_add_f32_e32 v201, 0xc1880000, v181
	v_add_f32_e32 v202, 0xc1900000, v181
	v_add_f32_e32 v203, 0xc1980000, v181
	v_mul_f32_e32 v208, v126, v200
	v_mul_f32_e32 v209, v126, v201
	v_mul_f32_e32 v210, v126, v202
	v_mul_f32_e32 v211, v126, v203
	v_mul_f32_e64 v212, v200, -v127
	v_mul_f32_e64 v213, v201, -v127
	v_mul_f32_e64 v214, v202, -v127
	v_mul_f32_e64 v215, v203, -v127
	v_min_f32_e32 v208, v208, v212
	v_min_f32_e32 v209, v209, v213
	v_min_f32_e32 v210, v210, v214
	v_min_f32_e32 v211, v211, v215
	v_exp_f32_e32 v208, v208
	v_exp_f32_e32 v209, v209
	v_exp_f32_e32 v210, v210
	v_exp_f32_e32 v211, v211
	v_mul_f32_e32 v196, v208, v108
	v_mul_f32_e32 v197, v209, v109
	v_mul_f32_e32 v198, v210, v110
	v_mul_f32_e32 v199, v211, v111
	v_cndmask_b32_e64 v196, 0, v196, s[4:5]
	v_cndmask_b32_e64 v197, 0, v197, s[4:5]
	v_cndmask_b32_e64 v198, 0, v198, s[4:5]
	v_cndmask_b32_e64 v199, 0, v199, s[4:5]
	v_cvt_pk_bf16_f32 v102, v184, v185
	v_cvt_pk_bf16_f32 v103, v186, v187
	v_cvt_pk_bf16_f32 v104, v188, v189
	v_cvt_pk_bf16_f32 v105, v190, v191
	v_cvt_pk_bf16_f32 v106, v192, v193
	v_cvt_pk_bf16_f32 v107, v194, v195
	v_cvt_pk_bf16_f32 v108, v196, v197
	v_cvt_pk_bf16_f32 v109, v198, v199
	s_waitcnt lgkmcnt(0)
	v_mfma_f32_16x16x32_bf16 v[72:75], v[102:105], v[148:151], v[72:75]
	v_mfma_f32_16x16x32_bf16 v[56:59], v[106:109], v[148:151], v[56:59]
	v_mfma_f32_16x16x32_bf16 v[88:91], v[102:105], v[152:155], v[88:91]
	v_mfma_f32_16x16x32_bf16 v[52:55], v[106:109], v[152:155], v[52:55]
	v_mfma_f32_16x16x32_bf16 v[84:87], v[102:105], v[156:159], v[84:87]
	v_mfma_f32_16x16x32_bf16 v[48:51], v[106:109], v[156:159], v[48:51]
	v_mfma_f32_16x16x32_bf16 v[80:83], v[102:105], v[160:163], v[80:83]
	v_mfma_f32_16x16x32_bf16 v[44:47], v[106:109], v[160:163], v[44:47]
	s_and_saveexec_b64 s[4:5], s[8:9]
	s_cbranch_execz .LBB0_424
	v_add_u32_e32 v0, v129, v116
	s_waitcnt vmcnt(2)
	ds_write_b128 v0, v[24:27] offset:29184
; #define RT_COMMIT(KR, VR, buf) do { LAS unsigned char* bb_ = lds + (buf) * MX_BUF; \
;         if (kcopy) *(LAS u32x4*)(bb_ + krow * KP + kch * 16) = KR; *(LAS u32x4*)(bb_ + MX_KBYTES + vr * VP + vc * 16) = VR; } while (0)
; __device__ __forceinline__ void wg_ret_task(ParamsCP pp, int layer, LAS unsigned char* lds, int b, int h, int qb, int tid_in) {
;     ...
;         RT_ISSUE(kr0s, vr0s, st + 2); RT_COMPUTE(st, 0); RT_COMMIT(kr1s, vr1s, 1); __syncthreads();
;         if (st + 1 < 65) { RT_ISSUE(kr1s, vr1s, st + 3); RT_COMPUTE(st + 1, 1); RT_COMMIT(kr0s, vr0s, 0); __syncthreads(); }
.LBB0_424:
	s_or_b64 exec, exec, s[4:5]
	s_waitcnt vmcnt(1)
	ds_write_b128 v125, v[92:95] offset:37888
	v_mfma_f32_16x16x32_bf16 v[76:79], v[102:105], v[164:167], v[76:79]
	v_mfma_f32_16x16x32_bf16 v[40:43], v[106:109], v[164:167], v[40:43]
	v_mfma_f32_16x16x32_bf16 v[68:71], v[102:105], v[168:171], v[68:71]
	v_mfma_f32_16x16x32_bf16 v[36:39], v[106:109], v[168:171], v[36:39]
	v_mfma_f32_16x16x32_bf16 v[64:67], v[102:105], v[172:175], v[64:67]
	v_mfma_f32_16x16x32_bf16 v[32:35], v[106:109], v[172:175], v[32:35]
	v_mfma_f32_16x16x32_bf16 v[60:63], v[102:105], v[176:179], v[60:63]
	v_mfma_f32_16x16x32_bf16 v[28:31], v[106:109], v[176:179], v[28:31]
	s_add_i32 s4, s61, 1
	s_cmp_gt_u32 s4, 64
	s_waitcnt lgkmcnt(0)
	s_barrier
	s_cbranch_scc1 .LBB0_405
	s_min_u32 s4, s61, 61
	s_lshl_b32 s4, s4, 5
	s_add_i32 s14, s4, s39
	s_addk_i32 s4, 0x70
	s_cmp_lt_u32 s61, 61
	s_cselect_b32 s15, s4, 0x800
	s_add_i32 s15, s15, s49
	s_and_saveexec_b64 s[4:5], s[8:9]
	s_cbranch_execz .LBB0_427
	v_add_u32_e32 v0, s14, v123
	v_add_u32_e32 v2, s15, v128
	v_cndmask_b32_e64 v0, v2, v0, s[12:13]
	v_lshlrev_b64 v[2:3], 12, v[0:1]
	v_lshl_add_u64 v[2:3], v[120:121], 0, v[2:3]
	global_load_dwordx4 v[24:27], v[2:3], off
; #define RT_COMMIT(KR, VR, buf) do { LAS unsigned char* bb_ = lds + (buf) * MX_BUF; \
;         if (kcopy) *(LAS u32x4*)(bb_ + krow * KP + kch * 16) = KR; *(LAS u32x4*)(bb_ + MX_KBYTES + vr * VP + vc * 16) = VR; } while (0)
; __device__ __forceinline__ void wg_ret_task(ParamsCP pp, int layer, LAS unsigned char* lds, int b, int h, int qb, int tid_in) {
;     ...
;     __syncthreads();
;     RT_ISSUE(kr0s, vr0s, 0); RT_COMMIT(kr0s, vr0s, 0); RT_ISSUE(kr1s, vr1s, 1);
;     __syncthreads();
; #pragma unroll 1
;     for (int st = 0; st < 65; st += 2) {
;         RT_ISSUE(kr0s, vr0s, st + 2); RT_COMPUTE(st, 0); RT_COMMIT(kr1s, vr1s, 1); __syncthreads();
;         if (st + 1 < 65) { RT_ISSUE(kr1s, vr1s, st + 3); RT_COMPUTE(st + 1, 1); RT_COMMIT(kr0s, vr0s, 0); __syncthreads(); }
.LBB0_427:
	s_or_b64 exec, exec, s[4:5]
	v_mov_b32_e32 v0, s15
	v_mov_b32_e32 v2, s14
	v_cndmask_b32_e64 v0, v0, v2, s[10:11]
	v_or_b32_e32 v0, v0, v124
	v_lshl_add_u64 v[2:3], v[0:1], 1, v[118:119]
	global_load_dwordx4 v[92:95], v[2:3], off
	ds_read_b128 v[100:103], v134 offset:29184
	ds_read_b128 v[138:141], v134 offset:31488
	ds_read_b128 v[104:107], v134 offset:29248
	ds_read_b128 v[142:145], v134 offset:31552
	s_waitcnt lgkmcnt(3)
	v_mfma_f32_16x16x32_bf16 v[108:111], v[100:103], v[4:7], 0
	v_mfma_f32_16x16x32_bf16 v[100:103], v[100:103], v[12:15], 0
	s_waitcnt lgkmcnt(1)
	v_mfma_f32_16x16x32_bf16 v[112:115], v[104:107], v[8:11], v[108:111]
	v_mfma_f32_16x16x32_bf16 v[108:111], v[138:141], v[4:7], 0
	v_mfma_f32_16x16x32_bf16 v[104:107], v[104:107], v[16:19], v[100:103]
	v_mfma_f32_16x16x32_bf16 v[100:103], v[138:141], v[12:15], 0
	s_waitcnt lgkmcnt(0)
	v_mfma_f32_16x16x32_bf16 v[108:111], v[142:145], v[8:11], v[108:111]
	v_mfma_f32_16x16x32_bf16 v[100:103], v[142:145], v[16:19], v[100:103]
	ds_read_b64 v[148:149], v135 offset:37888
	ds_read_b64 v[150:151], v135 offset:37920
	ds_read_b64 v[152:153], v135 offset:39168
	ds_read_b64 v[154:155], v135 offset:39200
	ds_read_b64 v[156:157], v135 offset:40448
	ds_read_b64 v[158:159], v135 offset:40480
	ds_read_b64 v[160:161], v135 offset:41728
	ds_read_b64 v[162:163], v135 offset:41760
	ds_read_b64 v[164:165], v135 offset:43008
	ds_read_b64 v[166:167], v135 offset:43040
	ds_read_b64 v[168:169], v135 offset:44288
	ds_read_b64 v[170:171], v135 offset:44320
	ds_read_b64 v[172:173], v135 offset:45568
	ds_read_b64 v[174:175], v135 offset:45600
	v_cvt_f32_i32_e32 v180, v137
	v_cvt_f32_i32_e32 v181, v136
	v_add_f32_e32 v200, 0xc2000000, v180
	v_add_f32_e32 v201, 0xc2040000, v180
	v_add_f32_e32 v202, 0xc2080000, v180
	v_add_f32_e32 v203, 0xc20c0000, v180
	v_mul_f32_e32 v208, v126, v200
	v_mul_f32_e32 v209, v126, v201
	v_mul_f32_e32 v210, v126, v202
	v_mul_f32_e32 v211, v126, v203
	v_mul_f32_e64 v212, v200, -v127
	v_mul_f32_e64 v213, v201, -v127
	v_mul_f32_e64 v214, v202, -v127
	v_mul_f32_e64 v215, v203, -v127
	v_min_f32_e32 v208, v208, v212
	v_min_f32_e32 v209, v209, v213
	v_min_f32_e32 v210, v210, v214
	v_min_f32_e32 v211, v211, v215
	v_exp_f32_e32 v208, v208
	v_exp_f32_e32 v209, v209
	v_exp_f32_e32 v210, v210
	v_exp_f32_e32 v211, v211
	v_mul_f32_e32 v184, v208, v112
	v_mul_f32_e32 v185, v209, v113
	v_mul_f32_e32 v186, v210, v114
	v_mul_f32_e32 v187, v211, v115
	v_add_f32_e32 v200, 0xc2400000, v180
	v_add_f32_e32 v201, 0xc2440000, v180
	v_add_f32_e32 v202, 0xc2480000, v180
	v_add_f32_e32 v203, 0xc24c0000, v180
	v_mul_f32_e32 v208, v126, v200
	v_mul_f32_e32 v209, v126, v201
	v_mul_f32_e32 v210, v126, v202
	v_mul_f32_e32 v211, v126, v203
	v_mul_f32_e64 v212, v200, -v127
	v_mul_f32_e64 v213, v201, -v127
	v_mul_f32_e64 v214, v202, -v127
	v_mul_f32_e64 v215, v203, -v127
	v_min_f32_e32 v208, v208, v212
	v_min_f32_e32 v209, v209, v213
	v_min_f32_e32 v210, v210, v214
	v_min_f32_e32 v211, v211, v215
	v_exp_f32_e32 v208, v208
	v_exp_f32_e32 v209, v209
	v_exp_f32_e32 v210, v210
	v_exp_f32_e32 v211, v211
	v_mul_f32_e32 v188, v208, v108
	v_mul_f32_e32 v189, v209, v109
	v_mul_f32_e32 v190, v210, v110
	v_mul_f32_e32 v191, v211, v111
	s_waitcnt lgkmcnt(13)
	ds_read_b64 v[176:177], v135 offset:46848
	ds_read_b64 v[178:179], v135 offset:46880
	v_add_f32_e32 v200, 0xc2000000, v181
	v_add_f32_e32 v201, 0xc2040000, v181
	v_add_f32_e32 v202, 0xc2080000, v181
	v_add_f32_e32 v203, 0xc20c0000, v181
	v_mul_f32_e32 v208, v126, v200
	v_mul_f32_e32 v209, v126, v201
	v_mul_f32_e32 v210, v126, v202
	v_mul_f32_e32 v211, v126, v203
	v_mul_f32_e64 v212, v200, -v127
	v_mul_f32_e64 v213, v201, -v127
	v_mul_f32_e64 v214, v202, -v127
	v_mul_f32_e64 v215, v203, -v127
	v_min_f32_e32 v208, v208, v212
	v_min_f32_e32 v209, v209, v213
	v_min_f32_e32 v210, v210, v214
	v_min_f32_e32 v211, v211, v215
	v_exp_f32_e32 v208, v208
	v_exp_f32_e32 v209, v209
	v_exp_f32_e32 v210, v210
	v_exp_f32_e32 v211, v211
	v_mul_f32_e32 v192, v208, v104
	v_mul_f32_e32 v193, v209, v105
	v_mul_f32_e32 v194, v210, v106
	v_mul_f32_e32 v195, v211, v107
	v_add_f32_e32 v200, 0xc2400000, v181
	v_add_f32_e32 v201, 0xc2440000, v181
	v_add_f32_e32 v202, 0xc2480000, v181
	v_add_f32_e32 v203, 0xc24c0000, v181
	v_mul_f32_e32 v208, v126, v200
	v_mul_f32_e32 v209, v126, v201
	v_mul_f32_e32 v210, v126, v202
	v_mul_f32_e32 v211, v126, v203
	v_mul_f32_e64 v212, v200, -v127
	v_mul_f32_e64 v213, v201, -v127
	v_mul_f32_e64 v214, v202, -v127
	v_mul_f32_e64 v215, v203, -v127
	v_min_f32_e32 v208, v208, v212
	v_min_f32_e32 v209, v209, v213
	v_min_f32_e32 v210, v210, v214
	v_min_f32_e32 v211, v211, v215
	v_exp_f32_e32 v208, v208
	v_exp_f32_e32 v209, v209
	v_exp_f32_e32 v210, v210
	v_exp_f32_e32 v211, v211
	v_mul_f32_e32 v196, v208, v100
	v_mul_f32_e32 v197, v209, v101
	v_mul_f32_e32 v198, v210, v102
	v_mul_f32_e32 v199, v211, v103
	v_cvt_pk_bf16_f32 v106, v184, v185
	v_cvt_pk_bf16_f32 v107, v186, v187
	v_cvt_pk_bf16_f32 v108, v188, v189
	v_cvt_pk_bf16_f32 v109, v190, v191
	v_cvt_pk_bf16_f32 v102, v192, v193
	v_cvt_pk_bf16_f32 v103, v194, v195
	v_cvt_pk_bf16_f32 v104, v196, v197
	v_cvt_pk_bf16_f32 v105, v198, v199
	s_waitcnt lgkmcnt(0)
	v_mfma_f32_16x16x32_bf16 v[72:75], v[106:109], v[148:151], v[72:75]
	v_mfma_f32_16x16x32_bf16 v[56:59], v[102:105], v[148:151], v[56:59]
	v_mfma_f32_16x16x32_bf16 v[88:91], v[106:109], v[152:155], v[88:91]
	v_mfma_f32_16x16x32_bf16 v[52:55], v[102:105], v[152:155], v[52:55]
	v_mfma_f32_16x16x32_bf16 v[84:87], v[106:109], v[156:159], v[84:87]
	v_mfma_f32_16x16x32_bf16 v[48:51], v[102:105], v[156:159], v[48:51]
	v_mfma_f32_16x16x32_bf16 v[80:83], v[106:109], v[160:163], v[80:83]
	v_mfma_f32_16x16x32_bf16 v[44:47], v[102:105], v[160:163], v[44:47]
	s_and_saveexec_b64 s[4:5], s[8:9]
	s_cbranch_execz .Lr_b_skipk
	v_add_u32_e32 v0, v129, v116
	ds_write_b128 v0, v[20:23]
.Lr_b_skipk:
	s_or_b64 exec, exec, s[4:5]
	s_waitcnt vmcnt(1)
	ds_write_b128 v125, v[96:99] offset:8704
	v_mfma_f32_16x16x32_bf16 v[76:79], v[106:109], v[164:167], v[76:79]
	v_mfma_f32_16x16x32_bf16 v[40:43], v[102:105], v[164:167], v[40:43]
	v_mfma_f32_16x16x32_bf16 v[68:71], v[106:109], v[168:171], v[68:71]
	v_mfma_f32_16x16x32_bf16 v[36:39], v[102:105], v[168:171], v[36:39]
	v_mfma_f32_16x16x32_bf16 v[64:67], v[106:109], v[172:175], v[64:67]
	v_mfma_f32_16x16x32_bf16 v[32:35], v[102:105], v[172:175], v[32:35]
	v_mfma_f32_16x16x32_bf16 v[60:63], v[106:109], v[176:179], v[60:63]
	v_mfma_f32_16x16x32_bf16 v[28:31], v[102:105], v[176:179], v[28:31]
	s_branch .LBB0_404

; #define LAS __attribute__((address_space(3)))
; __device__ __forceinline__ float fast_exp2(float x) { return __builtin_amdgcn_exp2f(x); }
; __device__ __forceinline__ void wg_diff_task(ParamsCP pp, int layer, LAS unsigned char* lds, int b, int h, int qb, int tid_in) {
;     ...
;     for (int st = 0; st < 65; ++st) {
;         const int buf = st & 1;
;         if (st + 1 < 65) DF_ISSUE(st + 1);
;         const LAS unsigned char* kb = lds + buf * DF_BUF; const LAS unsigned char* vb = kb + DF_KBYTES;
;         const bool v1 = 2 * st + 1 < 129;
;         bf16x8 pf0, pf1;
;         {   bf16x8 k0[4], k1[4];
; #pragma unroll
;             for (int ks = 0; ks < 4; ++ks) { k0[ks] = *(const LAS bf16x8*)(kb + c16 * DF_KP + (32 * ks + 8 * quad) * 2); k1[ks] = *(const LAS bf16x8*)(kb + (16 + c16) * DF_KP + (32 * ks + 8 * quad) * 2); }
;             const f32x4 s0 = st_mma<4>(k0, qf0), s1 = st_mma<4>(k1, qf0);
;             float p0[4], p1[4];
; #pragma unroll
;             for (int r = 0; r < 4; ++r) { p0[r] = fast_exp2(s0[r] * sc - cb); p1[r] = v1 ? fast_exp2(s1[r] * sc - cb) : 0.f; ls0 += p0[r] + p1[r]; }
;             pf0 = pack_p(p0, p1); }
;         {   bf16x8 k0[4], k1[4];
; #pragma unroll
;             for (int ks = 0; ks < 4; ++ks) { k0[ks] = *(const LAS bf16x8*)(kb + c16 * DF_KP + 256 + (32 * ks + 8 * quad) * 2); k1[ks] = *(const LAS bf16x8*)(kb + (16 + c16) * DF_KP + 256 + (32 * ks + 8 * quad) * 2); }
;             const f32x4 s0 = st_mma<4>(k0, qf1), s1 = st_mma<4>(k1, qf1);
;             float p0[4], p1[4];
; #pragma unroll
;             for (int r = 0; r < 4; ++r) { p0[r] = fast_exp2(s0[r] * sc - cb); p1[r] = v1 ? fast_exp2(s1[r] * sc - cb) : 0.f; ls1 += p0[r] + p1[r]; }
;             pf1 = pack_p(p0, p1); }
.LBB0_442:
	s_and_b32 s41, s39, 1
	s_mul_i32 s50, s41, 0x9200
	v_add3_u32 v219, s50, v217, v0
	ds_read_b128 v[190:193], v219
	ds_read_b128 v[194:197], v219 offset:64
	ds_read_b128 v[198:201], v219 offset:8448
	ds_read_b128 v[202:205], v219 offset:8512
	s_cmp_eq_u32 s39, 64
	s_cselect_b64 s[48:49], -1, 0
	s_cmp_lg_u32 s39, 64
	s_cselect_b64 s[4:5], -1, 0
	s_and_b64 vcc, exec, s[48:49]
	s_cbranch_vccnz .LBB0_444
	s_min_u32 s41, s38, 0x80
	s_lshl_b32 s41, s41, 4
	s_add_i32 s41, s41, s37
	s_waitcnt vmcnt(3)
	v_mov_b32_e32 v162, s41
	s_waitcnt vmcnt(1)
	v_mov_b32_e32 v172, s40
	v_cndmask_b32_e64 v162, v162, v172, s[8:9]
	s_add_i32 s50, s41, -16
	v_or_b32_e32 v162, v162, v181
	v_ashrrev_i32_e32 v163, 31, v162
	v_mov_b32_e32 v173, s50
	v_lshl_add_u64 v[170:171], v[162:163], 1, s[16:17]
	v_cndmask_b32_e64 v162, v173, v172, s[10:11]
	v_cndmask_b32_e64 v172, v173, v172, s[12:13]
	v_add_u32_e32 v162, v162, v209
	v_add_u32_e32 v172, v172, v210
	v_ashrrev_i32_e32 v163, 31, v162
	v_ashrrev_i32_e32 v173, 31, v172
	v_lshlrev_b64 v[162:163], 12, v[162:163]
	v_lshlrev_b64 v[172:173], 12, v[172:173]
	v_lshl_add_u64 v[162:163], v[182:183], 0, v[162:163]
	v_lshl_add_u64 v[166:167], v[170:171], 0, v[184:185]
	v_lshl_add_u64 v[172:173], v[182:183], 0, v[172:173]
	s_waitcnt vmcnt(0)
	v_lshl_add_u64 v[174:175], v[170:171], 0, v[186:187]
	global_load_dwordx4 v[162:165], v[162:163], off
	s_nop 0
	global_load_dwordx4 v[166:169], v[166:167], off
	s_nop 0
	global_load_dwordx4 v[170:173], v[172:173], off
	s_nop 0
	global_load_dwordx4 v[174:177], v[174:175], off
.LBB0_444:
	s_and_b32 s41, s39, 1
	s_mul_i32 s50, s41, 0x9200
	s_add_i32 s50, s50, 0
	s_andn2_b64 vcc, exec, s[4:5]
	s_waitcnt lgkmcnt(3)
	v_mfma_f32_16x16x32_bf16 v[190:193], v[190:193], v[114:117], 0
	s_waitcnt lgkmcnt(2)
	v_mfma_f32_16x16x32_bf16 v[190:193], v[194:197], v[118:121], v[190:193]
	ds_read_b128 v[194:197], v219 offset:128
	s_waitcnt lgkmcnt(2)
	v_mfma_f32_16x16x32_bf16 v[198:201], v[198:201], v[114:117], 0
	s_waitcnt lgkmcnt(1)
	v_mfma_f32_16x16x32_bf16 v[198:201], v[202:205], v[118:121], v[198:201]
	ds_read_b128 v[202:205], v219 offset:192
	s_waitcnt lgkmcnt(1)
	v_mfma_f32_16x16x32_bf16 v[190:193], v[194:197], v[134:137], v[190:193]
	ds_read_b128 v[194:197], v219 offset:8576
	s_waitcnt lgkmcnt(1)
	v_mfma_f32_16x16x32_bf16 v[202:205], v[202:205], v[138:141], v[190:193]
	s_nop 4
	ds_read_b128 v[190:193], v219 offset:8640
	s_waitcnt lgkmcnt(1)
	v_mfma_f32_16x16x32_bf16 v[194:197], v[194:197], v[134:137], v[198:201]
	s_nop 2
	ds_read_b128 v[198:201], v219 offset:256
	ds_read_b128 v[242:245], v219 offset:320
	ds_read_b128 v[246:249], v219 offset:384
	ds_read_b128 v[250:253], v219 offset:448
	s_waitcnt lgkmcnt(3)
	v_mfma_f32_16x16x32_bf16 v[198:201], v[198:201], v[122:125], 0
	ds_read_b128 v[232:235], v219 offset:8896
	s_waitcnt lgkmcnt(3)
	v_mfma_f32_16x16x32_bf16 v[198:201], v[242:245], v[126:129], v[198:201]
	ds_read_b128 v[242:245], v219 offset:8704
	s_waitcnt lgkmcnt(3)
	v_mfma_f32_16x16x32_bf16 v[198:201], v[246:249], v[142:145], v[198:201]
	ds_read_b128 v[246:249], v219 offset:8768
	v_mfma_f32_16x16x32_bf16 v[194:197], v[190:193], v[138:141], v[194:197]
	v_fma_f32 v190, v202, s89, -v179
	v_exp_f32_e32 v190, v190
	s_waitcnt lgkmcnt(3)
	v_mfma_f32_16x16x32_bf16 v[198:201], v[250:253], v[146:149], v[198:201]
	ds_read_b128 v[250:253], v219 offset:8832
	s_nop 2
	v_fma_f32 v191, v194, s89, -v179
	v_exp_f32_e32 v220, v191
	s_waitcnt lgkmcnt(2)
	v_mfma_f32_16x16x32_bf16 v[242:245], v[242:245], v[122:125], 0
	v_fma_f32 v191, v203, s89, -v179
	v_exp_f32_e32 v192, v191
	v_fma_f32 v191, v195, s89, -v179
	s_waitcnt lgkmcnt(1)
	v_mfma_f32_16x16x32_bf16 v[242:245], v[246:249], v[126:129], v[242:245]
	v_exp_f32_e32 v221, v191
	v_fma_f32 v191, v204, s89, -v179
	v_exp_f32_e32 v194, v191
	v_fma_f32 v191, v196, s89, -v179
	v_exp_f32_e32 v224, v191
	v_fma_f32 v191, v205, s89, -v179
	s_waitcnt lgkmcnt(0)
	v_mfma_f32_16x16x32_bf16 v[202:205], v[250:253], v[142:145], v[242:245]
	v_exp_f32_e32 v196, v191
	v_fma_f32 v191, v197, s89, -v179
	v_exp_f32_e32 v219, v191
	v_mfma_f32_16x16x32_bf16 v[202:205], v[232:235], v[146:149], v[202:205]
	v_fma_f32 v191, v198, s89, -v179
	v_exp_f32_e32 v191, v191
	v_add3_u32 v250, s50, v218, v211
	v_add_u32_e32 v251, 0x4000, v250
	v_cvt_pk_bf16_f32 v242, v190, v192
	s_nop 2
	v_fma_f32 v193, v202, s89, -v179
	v_exp_f32_e32 v198, v193
	v_fma_f32 v193, v199, s89, -v179
	v_fma_f32 v195, v203, s89, -v179
	v_fma_f32 v197, v204, s89, -v179
	v_fma_f32 v199, v205, s89, -v179
	v_exp_f32_e32 v203, v195
	v_fma_f32 v195, v200, s89, -v179
	v_exp_f32_e32 v234, v197
	v_fma_f32 v197, v201, s89, -v179
	v_exp_f32_e32 v205, v199
	v_exp_f32_e32 v193, v193
	v_exp_f32_e32 v195, v195
	v_exp_f32_e32 v197, v197
	v_cndmask_b32_e64 v199, v198, 0, s[48:49]
	v_cndmask_b32_e64 v198, v220, 0, s[48:49]
	v_cndmask_b32_e64 v200, v221, 0, s[48:49]
	v_cndmask_b32_e64 v202, v224, 0, s[48:49]
	v_cndmask_b32_e64 v204, v219, 0, s[48:49]
	v_cndmask_b32_e64 v201, v203, 0, s[48:49]
	v_cndmask_b32_e64 v203, v234, 0, s[48:49]
	v_cndmask_b32_e64 v205, v205, 0, s[48:49]
	v_cvt_pk_bf16_f32 v243, v194, v196
	v_cvt_pk_bf16_f32 v232, v191, v193
	v_cvt_pk_bf16_f32 v233, v195, v197
	ds_read_b64 v[246:247], v250 offset:16896
	ds_read_b64 v[248:249], v250 offset:16928
	v_cvt_pk_bf16_f32 v244, v198, v200
	v_cvt_pk_bf16_f32 v245, v202, v204
	v_cvt_pk_bf16_f32 v234, v199, v201
	v_cvt_pk_bf16_f32 v235, v203, v205
	v_pk_add_f32 v[190:191], v[190:191], v[198:199]
	v_pk_add_f32 v[192:193], v[192:193], v[200:201]
	v_pk_add_f32 v[188:189], v[188:189], v[190:191]
	v_pk_add_f32 v[194:195], v[194:195], v[202:203]
	v_pk_add_f32 v[188:189], v[192:193], v[188:189]
	v_pk_add_f32 v[196:197], v[196:197], v[204:205]
	v_pk_add_f32 v[188:189], v[194:195], v[188:189]
	v_pk_add_f32 v[188:189], v[196:197], v[188:189]
	ds_read_b64 v[190:191], v250 offset:18176
	ds_read_b64 v[192:193], v250 offset:18208
	ds_read_b64 v[194:195], v250 offset:19456
	ds_read_b64 v[196:197], v250 offset:19488
	ds_read_b64 v[198:199], v250 offset:20736
	ds_read_b64 v[200:201], v250 offset:20768
	ds_read_b64 v[202:203], v250 offset:22016
	ds_read_b64 v[204:205], v250 offset:22048
	s_waitcnt lgkmcnt(8)
; #define LAS __attribute__((address_space(3)))
; __device__ __forceinline__ f32x4 mfma16(bf16x8 a, bf16x8 b, f32x4 c) { return __builtin_amdgcn_mfma_f32_16x16x32_bf16(a, b, c, 0, 0, 0); }
; #define DF_COMMIT(buf) do { LAS unsigned char* bb_ = lds + (buf) * DF_BUF; \
;         _Pragma("unroll") for (int i_ = 0; i_ < 2; ++i_) { const int id_ = tid + 512 * i_, kr_ = id_ >> 5, kc_ = id_ & 31, vr_ = id_ >> 2, vc_ = id_ & 3; \
;             *(LAS u32x4*)(bb_ + kr_ * DF_KP + kc_ * 16) = kreg[i_]; *(LAS u32x4*)(bb_ + DF_KBYTES + vr_ * VP + vc_ * 16) = vreg[i_]; } } while (0)
; __device__ __forceinline__ void wg_diff_task(ParamsCP pp, int layer, LAS unsigned char* lds, int b, int h, int qb, int tid_in) {
;     ...
; #pragma unroll
;         for (int e0 = 0; e0 < 16; ++e0) {
;             const u32x2 va = *(const LAS u32x2*)(vb + (e0 * 16 + c16) * VP + 8 * quad), vbb = *(const LAS u32x2*)(vb + (e0 * 16 + c16) * VP + 32 + 8 * quad);
;             u32x4 w; w.x = va.x; w.y = va.y; w.z = vbb.x; w.w = vbb.y; const bf16x8 vf = __builtin_bit_cast(bf16x8, w);
;             acc0[e0] = mfma16(pf0, vf, acc0[e0]); acc1[e0] = mfma16(pf1, vf, acc1[e0]);
;         }
;         if (st + 1 < 65) DF_COMMIT(buf ^ 1);
;         __syncthreads();
	v_mfma_f32_16x16x32_bf16 v[158:161], v[242:245], v[246:249], v[158:161]
	v_mfma_f32_16x16x32_bf16 v[130:133], v[232:235], v[246:249], v[130:133]
	ds_read_b64 v[246:247], v250 offset:23296
	ds_read_b64 v[248:249], v250 offset:23328
	s_waitcnt lgkmcnt(8)
	v_mfma_f32_16x16x32_bf16 v[154:157], v[242:245], v[190:193], v[154:157]
	v_mfma_f32_16x16x32_bf16 v[102:105], v[232:235], v[190:193], v[102:105]
	ds_read_b64 v[190:191], v250 offset:24576
	ds_read_b64 v[192:193], v250 offset:24608
	s_waitcnt lgkmcnt(8)
	v_mfma_f32_16x16x32_bf16 v[150:153], v[242:245], v[194:197], v[150:153]
	v_mfma_f32_16x16x32_bf16 v[90:93], v[232:235], v[194:197], v[90:93]
	ds_read_b64 v[194:195], v250 offset:25856
	ds_read_b64 v[196:197], v250 offset:25888
	s_waitcnt lgkmcnt(8)
	v_mfma_f32_16x16x32_bf16 v[110:113], v[242:245], v[198:201], v[110:113]
	v_mfma_f32_16x16x32_bf16 v[82:85], v[232:235], v[198:201], v[82:85]
	ds_read_b64 v[198:199], v250 offset:27136
	ds_read_b64 v[200:201], v250 offset:27168
	s_waitcnt lgkmcnt(8)
	v_mfma_f32_16x16x32_bf16 v[106:109], v[242:245], v[202:205], v[106:109]
	v_mfma_f32_16x16x32_bf16 v[70:73], v[232:235], v[202:205], v[70:73]
	ds_read_b64 v[202:203], v250 offset:28416
	ds_read_b64 v[204:205], v250 offset:28448
	s_waitcnt lgkmcnt(8)
	v_mfma_f32_16x16x32_bf16 v[98:101], v[242:245], v[246:249], v[98:101]
	v_mfma_f32_16x16x32_bf16 v[58:61], v[232:235], v[246:249], v[58:61]
	ds_read_b64 v[246:247], v250 offset:29696
	ds_read_b64 v[248:249], v250 offset:29728
	s_waitcnt lgkmcnt(8)
	v_mfma_f32_16x16x32_bf16 v[94:97], v[242:245], v[190:193], v[94:97]
	v_mfma_f32_16x16x32_bf16 v[50:53], v[232:235], v[190:193], v[50:53]
	ds_read_b64 v[190:191], v250 offset:30976
	ds_read_b64 v[192:193], v250 offset:31008
	s_waitcnt lgkmcnt(8)
	v_mfma_f32_16x16x32_bf16 v[86:89], v[242:245], v[194:197], v[86:89]
	v_mfma_f32_16x16x32_bf16 v[22:25], v[232:235], v[194:197], v[22:25]
	ds_read_b64 v[194:195], v250 offset:32256
	ds_read_b64 v[196:197], v250 offset:32288
	s_waitcnt lgkmcnt(8)
	v_mfma_f32_16x16x32_bf16 v[78:81], v[242:245], v[198:201], v[78:81]
	v_mfma_f32_16x16x32_bf16 v[42:45], v[232:235], v[198:201], v[42:45]
	ds_read_b64 v[198:199], v250 offset:33536
	ds_read_b64 v[200:201], v250 offset:33568
	s_waitcnt lgkmcnt(8)
	v_mfma_f32_16x16x32_bf16 v[74:77], v[242:245], v[202:205], v[74:77]
	v_mfma_f32_16x16x32_bf16 v[34:37], v[232:235], v[202:205], v[34:37]
	ds_read_b64 v[202:203], v250 offset:34816
	ds_read_b64 v[204:205], v250 offset:34848
	s_waitcnt lgkmcnt(8)
	v_mfma_f32_16x16x32_bf16 v[66:69], v[242:245], v[246:249], v[66:69]
	v_mfma_f32_16x16x32_bf16 v[26:29], v[232:235], v[246:249], v[26:29]
	ds_read_b64 v[246:247], v250 offset:36096
	ds_read_b64 v[248:249], v250 offset:36128
	s_cbranch_vccnz .Ldf_tail_nw
	s_xor_b32 s4, s41, 1
	s_mul_i32 s4, s4, 0x9200
	s_add_i32 s4, s4, 0
	v_add_u32_e32 v219, s4, v180
	v_add_u32_e32 v220, v219, v213
	v_add_u32_e32 v221, s4, v212
	v_add_u32_e32 v224, v221, v214
	v_add_u32_e32 v219, v219, v215
	v_add_u32_e32 v221, v221, v216
	s_waitcnt lgkmcnt(8)
	v_mfma_f32_16x16x32_bf16 v[62:65], v[242:245], v[190:193], v[62:65]
	v_mfma_f32_16x16x32_bf16 v[18:21], v[232:235], v[190:193], v[18:21]
	s_waitcnt vmcnt(3)
	ds_write_b128 v220, v[162:165]
	s_waitcnt lgkmcnt(7)
	v_mfma_f32_16x16x32_bf16 v[54:57], v[242:245], v[194:197], v[54:57]
	v_mfma_f32_16x16x32_bf16 v[14:17], v[232:235], v[194:197], v[14:17]
	s_waitcnt vmcnt(2)
	ds_write_b128 v224, v[166:169] offset:16896
	s_waitcnt lgkmcnt(6)
	v_mfma_f32_16x16x32_bf16 v[46:49], v[242:245], v[198:201], v[46:49]
	v_mfma_f32_16x16x32_bf16 v[10:13], v[232:235], v[198:201], v[10:13]
	s_waitcnt vmcnt(1)
	ds_write_b128 v219, v[170:173]
	s_waitcnt lgkmcnt(5)
	v_mfma_f32_16x16x32_bf16 v[38:41], v[242:245], v[202:205], v[38:41]
	v_mfma_f32_16x16x32_bf16 v[6:9], v[232:235], v[202:205], v[6:9]
	s_waitcnt vmcnt(0)
	ds_write_b128 v221, v[174:177] offset:16896
	s_waitcnt lgkmcnt(4)
	v_mfma_f32_16x16x32_bf16 v[30:33], v[242:245], v[246:249], v[30:33]
	v_mfma_f32_16x16x32_bf16 v[2:5], v[232:235], v[246:249], v[2:5]
	s_branch .LBB0_441
.Ldf_tail_nw:
	s_waitcnt lgkmcnt(8)
	v_mfma_f32_16x16x32_bf16 v[62:65], v[242:245], v[190:193], v[62:65]
	v_mfma_f32_16x16x32_bf16 v[18:21], v[232:235], v[190:193], v[18:21]
	s_waitcnt lgkmcnt(6)
	v_mfma_f32_16x16x32_bf16 v[54:57], v[242:245], v[194:197], v[54:57]
	v_mfma_f32_16x16x32_bf16 v[14:17], v[232:235], v[194:197], v[14:17]
	s_waitcnt lgkmcnt(4)
	v_mfma_f32_16x16x32_bf16 v[46:49], v[242:245], v[198:201], v[46:49]
	v_mfma_f32_16x16x32_bf16 v[10:13], v[232:235], v[198:201], v[10:13]
	s_waitcnt lgkmcnt(2)
	v_mfma_f32_16x16x32_bf16 v[38:41], v[242:245], v[202:205], v[38:41]
	v_mfma_f32_16x16x32_bf16 v[6:9], v[232:235], v[202:205], v[6:9]
	s_waitcnt lgkmcnt(0)
	v_mfma_f32_16x16x32_bf16 v[30:33], v[242:245], v[246:249], v[30:33]
	v_mfma_f32_16x16x32_bf16 v[2:5], v[232:235], v[246:249], v[2:5]
	s_branch .LBB0_441
